# HGRN2 prep: 64 serialized q,f element loads per half (each followed by vmcnt 0) replaced by one batched load block; plus GDN scan DMA split and LDS prefetch changes
# speedup vs baseline: 1.0233x; 1.0233x over previous
; #define GAS __attribute__((address_space(1)))
; DI void hgrn_prep_job(const Frame& F, int job, int layer, LAS unsigned char* scr) {
;     ...
;     for (int half = 0; half < 2; ++half) {
;         const int dk = 64 * half + lane;
;         const float lb = ((const GAS float*)lbs)[dk];
;         const GAS bf16* pq = (const GAS bf16*)(P + m0 * NP + PB_Q + h * 128 + dk); const GAS bf16* pf = (const GAS bf16*)(P + m0 * NP + PB_F + h * 128 + dk); const GAS bf16* pv = (const GAS bf16*)(P + m0 * NP + PB_I + h * 128 + dk);
;         unsigned short ve[32];
; #pragma unroll
;         for (int t = 0; t < 32; ++t) ve[t] = pv[(size_t)t * NP];
;         float bq[32], kv[32], qv[32]; float bsum = 0.f;
;         unsigned short qe[32], fe[32];
; #pragma unroll
;         for (int t = 0; t < 32; ++t) { qe[t] = pq[(size_t)t * NP]; fe[t] = pf[(size_t)t * NP]; }
.LBB0_810:
	v_or_b32_e32 v96, s0, v48
	v_lshlrev_b64 v[6:7], 1, v[96:97]
	v_lshl_add_u64 v[8:9], s[70:71], 0, v[6:7]
	v_lshl_add_u64 v[14:15], s[66:67], 0, v[6:7]
	v_lshl_add_u64 v[12:13], s[68:69], 0, v[6:7]
	v_mov_b32_e32 v139, v6
	global_load_ushort v141, v139, s[66:67] offset:3072
	global_load_ushort v173, v139, s[68:69]
	v_add_u32_e32 v140, 0x3c00, v139
	global_load_ushort v142, v140, s[66:67] offset:3072
	global_load_ushort v174, v140, s[68:69]
	v_add_u32_e32 v140, 0x7800, v139
	global_load_ushort v143, v140, s[66:67] offset:3072
	global_load_ushort v175, v140, s[68:69]
	v_add_u32_e32 v140, 0xb400, v139
	global_load_ushort v144, v140, s[66:67] offset:3072
	global_load_ushort v176, v140, s[68:69]
	v_add_u32_e32 v140, 0xf000, v139
	global_load_ushort v145, v140, s[66:67] offset:3072
	global_load_ushort v177, v140, s[68:69]
	v_add_u32_e32 v140, 0x12c00, v139
	global_load_ushort v146, v140, s[66:67] offset:3072
	global_load_ushort v178, v140, s[68:69]
	v_add_u32_e32 v140, 0x16800, v139
	global_load_ushort v147, v140, s[66:67] offset:3072
	global_load_ushort v179, v140, s[68:69]
	v_add_u32_e32 v140, 0x1a400, v139
	global_load_ushort v148, v140, s[66:67] offset:3072
	global_load_ushort v180, v140, s[68:69]
	v_add_u32_e32 v140, 0x1e000, v139
	global_load_ushort v149, v140, s[66:67] offset:3072
	global_load_ushort v181, v140, s[68:69]
	v_add_u32_e32 v140, 0x21c00, v139
	global_load_ushort v150, v140, s[66:67] offset:3072
	global_load_ushort v182, v140, s[68:69]
	v_add_u32_e32 v140, 0x25800, v139
	global_load_ushort v151, v140, s[66:67] offset:3072
	global_load_ushort v183, v140, s[68:69]
	v_add_u32_e32 v140, 0x29400, v139
	global_load_ushort v152, v140, s[66:67] offset:3072
	global_load_ushort v186, v140, s[68:69]
	v_add_u32_e32 v140, 0x2d000, v139
	global_load_ushort v153, v140, s[66:67] offset:3072
	global_load_ushort v187, v140, s[68:69]
	v_add_u32_e32 v140, 0x30c00, v139
	global_load_ushort v154, v140, s[66:67] offset:3072
	global_load_ushort v188, v140, s[68:69]
	v_add_u32_e32 v140, 0x34800, v139
	global_load_ushort v155, v140, s[66:67] offset:3072
	global_load_ushort v189, v140, s[68:69]
	v_add_u32_e32 v140, 0x38400, v139
	global_load_ushort v156, v140, s[66:67] offset:3072
	global_load_ushort v190, v140, s[68:69]
	v_add_u32_e32 v140, 0x3c000, v139
	global_load_ushort v157, v140, s[66:67] offset:3072
	global_load_ushort v191, v140, s[68:69]
	v_add_u32_e32 v140, 0x3fc00, v139
	global_load_ushort v158, v140, s[66:67] offset:3072
	global_load_ushort v192, v140, s[68:69]
	v_add_u32_e32 v140, 0x43800, v139
	global_load_ushort v159, v140, s[66:67] offset:3072
	global_load_ushort v193, v140, s[68:69]
	v_add_u32_e32 v140, 0x47400, v139
	global_load_ushort v160, v140, s[66:67] offset:3072
	global_load_ushort v194, v140, s[68:69]
	v_add_u32_e32 v140, 0x4b000, v139
	global_load_ushort v161, v140, s[66:67] offset:3072
	global_load_ushort v195, v140, s[68:69]
	v_add_u32_e32 v140, 0x4ec00, v139
	global_load_ushort v162, v140, s[66:67] offset:3072
	global_load_ushort v196, v140, s[68:69]
	v_add_u32_e32 v140, 0x52800, v139
	global_load_ushort v163, v140, s[66:67] offset:3072
	global_load_ushort v197, v140, s[68:69]
	v_add_u32_e32 v140, 0x56400, v139
	global_load_ushort v164, v140, s[66:67] offset:3072
	global_load_ushort v198, v140, s[68:69]
	v_add_u32_e32 v140, 0x5a000, v139
	global_load_ushort v165, v140, s[66:67] offset:3072
	global_load_ushort v199, v140, s[68:69]
	v_add_u32_e32 v140, 0x5dc00, v139
	global_load_ushort v166, v140, s[66:67] offset:3072
	global_load_ushort v200, v140, s[68:69]
	v_add_u32_e32 v140, 0x61800, v139
	global_load_ushort v167, v140, s[66:67] offset:3072
	global_load_ushort v201, v140, s[68:69]
	v_add_u32_e32 v140, 0x65400, v139
	global_load_ushort v168, v140, s[66:67] offset:3072
	global_load_ushort v202, v140, s[68:69]
	v_add_u32_e32 v140, 0x69000, v139
	global_load_ushort v169, v140, s[66:67] offset:3072
	global_load_ushort v203, v140, s[68:69]
	v_add_u32_e32 v140, 0x6cc00, v139
	global_load_ushort v170, v140, s[66:67] offset:3072
	global_load_ushort v204, v140, s[68:69]
	v_add_u32_e32 v140, 0x70800, v139
	global_load_ushort v171, v140, s[66:67] offset:3072
	global_load_ushort v205, v140, s[68:69]
	v_add_u32_e32 v140, 0x74400, v139
	global_load_ushort v172, v140, s[66:67] offset:3072
	global_load_ushort v206, v140, s[68:69]
	v_add_co_u32_e32 v6, vcc, 0x7000, v8
	v_lshlrev_b64 v[10:11], 2, v[96:97]
	s_nop 0
	v_addc_co_u32_e32 v7, vcc, 0, v9, vcc
	global_load_ushort v59, v[6:7], off offset:2048
	v_add_co_u32_e32 v6, vcc, 0xf000, v8
	v_lshl_add_u64 v[4:5], s[56:57], 0, v[10:11]
	s_nop 0
	v_addc_co_u32_e32 v7, vcc, 0, v9, vcc
	global_load_dword v4, v[4:5], off
	s_movk_i32 s0, 0x7000
	global_load_ushort v58, v[8:9], off
	global_load_ushort v60, v[6:7], off
	v_add_co_u32_e32 v6, vcc, s74, v8
	s_nop 0
	v_addc_co_u32_e32 v7, vcc, 0, v9, vcc
	global_load_ushort v61, v[6:7], off offset:2048
	v_add_co_u32_e32 v6, vcc, s89, v8
	v_lshl_add_u32 v119, v96, 1, s31
	s_nop 0
	v_addc_co_u32_e32 v7, vcc, 0, v9, vcc
	global_load_ushort v62, v[6:7], off
	v_add_co_u32_e32 v6, vcc, 0x25000, v8
	s_waitcnt vmcnt(2)
	s_waitcnt vmcnt(0)
; DI float bf2f(unsigned v) { return __uint_as_float(v << 16); }
; DI float flog(float x) { return __builtin_amdgcn_logf(x) * 0.6931471805599453f; }
; DI float sigm(float x) { return frcp(1.f + fexp(-x)); }
; DI float silu(float x) { return x * sigm(x); }
; DI void hgrn_prep_job(const Frame& F, int job, int layer, LAS unsigned char* scr) {
;     ...
; #pragma unroll
;         for (int t = 0; t < 32; ++t) {
;             const float qx = bf2f(qe[t]), fx = bf2f(fe[t]);
;             const float f = lb + (1.f - lb) * sigm(fx);
;             bsum += flog(f); bq[t] = bsum; kv[t] = 1.f - f; qv[t] = silu(qx);
;         }
	v_lshlrev_b32_e32 v5, 16, v141
	v_addc_co_u32_e32 v7, vcc, 0, v9, vcc
	global_load_ushort v63, v[6:7], off offset:2048
	v_add_co_u32_e32 v6, vcc, 0x2d000, v8
	s_nop 1
	v_addc_co_u32_e32 v7, vcc, 0, v9, vcc
	global_load_ushort v64, v[6:7], off
	v_add_co_u32_e32 v6, vcc, 0x34000, v8
	s_nop 1
	v_addc_co_u32_e32 v7, vcc, 0, v9, vcc
	global_load_ushort v65, v[6:7], off offset:2048
	v_add_co_u32_e32 v6, vcc, 0x3c000, v8
	s_nop 1
	v_addc_co_u32_e32 v7, vcc, 0, v9, vcc
	global_load_ushort v66, v[6:7], off
	v_add_co_u32_e32 v6, vcc, 0x43000, v8
	s_nop 1
	v_addc_co_u32_e32 v7, vcc, 0, v9, vcc
	global_load_ushort v67, v[6:7], off offset:2048
	v_add_co_u32_e32 v6, vcc, 0x4b000, v8
	s_nop 1
	v_addc_co_u32_e32 v7, vcc, 0, v9, vcc
	global_load_ushort v68, v[6:7], off
	v_add_co_u32_e32 v6, vcc, 0x52000, v8
	s_nop 1
	v_addc_co_u32_e32 v7, vcc, 0, v9, vcc
	global_load_ushort v69, v[6:7], off offset:2048
	v_add_co_u32_e32 v6, vcc, 0x5a000, v8
	s_nop 1
	v_addc_co_u32_e32 v7, vcc, 0, v9, vcc
	global_load_ushort v70, v[6:7], off
	v_add_co_u32_e32 v6, vcc, 0x61000, v8
	s_nop 1
	v_addc_co_u32_e32 v7, vcc, 0, v9, vcc
	global_load_ushort v71, v[6:7], off offset:2048
	v_add_co_u32_e32 v6, vcc, 0x69000, v8
	s_nop 1
	v_addc_co_u32_e32 v7, vcc, 0, v9, vcc
	global_load_ushort v72, v[6:7], off
	v_add_co_u32_e32 v6, vcc, 0x70000, v8
	s_nop 1
	v_addc_co_u32_e32 v7, vcc, 0, v9, vcc
	global_load_ushort v73, v[6:7], off offset:2048
	v_add_co_u32_e32 v18, vcc, s4, v14
	s_nop 0
	v_addc_co_u32_e32 v19, vcc, 0, v15, vcc
	v_sub_f32_e32 v6, 1.0, v4
	v_lshlrev_b32_e32 v7, 16, v173
	v_mul_f32_e32 v7, 0xbfb8aa3b, v7
	v_exp_f32_e32 v7, v7
	s_nop 0
	v_add_f32_e32 v7, 1.0, v7
	v_rcp_f32_e32 v16, v7
	v_mul_f32_e32 v7, 0xbfb8aa3b, v5
	v_exp_f32_e32 v7, v7
	s_nop 0
	v_add_f32_e32 v7, 1.0, v7
	v_rcp_f32_e32 v7, v7
	s_nop 0
	v_mul_f32_e32 v7, v7, v5
	v_add_co_u32_e32 v18, vcc, s14, v12
	v_lshlrev_b32_e32 v5, 16, v142
	v_addc_co_u32_e32 v19, vcc, 0, v13, vcc
	v_mul_f32_e32 v18, 0xbfb8aa3b, v5
	v_exp_f32_e32 v18, v18
	v_lshlrev_b32_e32 v17, 16, v174
	v_add_f32_e32 v18, 1.0, v18
	v_rcp_f32_e32 v18, v18
	v_mul_f32_e32 v17, 0xbfb8aa3b, v17
	v_exp_f32_e32 v17, v17
	v_mul_f32_e32 v5, v18, v5
	v_add_co_u32_e32 v18, vcc, s88, v14
	v_add_f32_e32 v17, 1.0, v17
	s_nop 0
	v_addc_co_u32_e32 v19, vcc, 0, v15, vcc
	v_rcp_f32_e32 v17, v17
	v_lshlrev_b32_e32 v20, 16, v143
	v_add_co_u32_e32 v18, vcc, s0, v12
	s_mov_b32 s0, 0xc000
	s_nop 0
	v_addc_co_u32_e32 v19, vcc, 0, v13, vcc
	v_lshlrev_b32_e32 v18, 16, v175
	v_mul_f32_e32 v18, 0xbfb8aa3b, v18
	v_exp_f32_e32 v18, v18
	s_nop 0
	v_add_f32_e32 v18, 1.0, v18
	v_rcp_f32_e32 v24, v18
	v_mul_f32_e32 v18, 0xbfb8aa3b, v20
	v_exp_f32_e32 v18, v18
	s_nop 0
	v_add_f32_e32 v18, 1.0, v18
	v_rcp_f32_e32 v18, v18
	s_nop 0
	v_mul_f32_e32 v74, v18, v20
	v_add_co_u32_e32 v18, vcc, s0, v14
	s_mov_b32 s0, 0x13000
	s_nop 0
	v_addc_co_u32_e32 v19, vcc, 0, v15, vcc
	v_lshlrev_b32_e32 v20, 16, v144
	v_add_co_u32_e32 v18, vcc, s15, v12
	s_nop 1
	v_addc_co_u32_e32 v19, vcc, 0, v13, vcc
	v_lshlrev_b32_e32 v18, 16, v176
	v_mul_f32_e32 v18, 0xbfb8aa3b, v18
	v_exp_f32_e32 v18, v18
	s_nop 0
	v_add_f32_e32 v18, 1.0, v18
	v_rcp_f32_e32 v25, v18
	v_mul_f32_e32 v18, 0xbfb8aa3b, v20
	v_exp_f32_e32 v18, v18
	s_nop 0
	v_add_f32_e32 v18, 1.0, v18
	v_rcp_f32_e32 v18, v18
	s_nop 0
	v_mul_f32_e32 v76, v18, v20
	v_add_co_u32_e32 v18, vcc, s8, v14
	s_nop 1
	v_addc_co_u32_e32 v19, vcc, 0, v15, vcc
	v_lshlrev_b32_e32 v20, 16, v145
	v_add_co_u32_e32 v18, vcc, s8, v12
	s_nop 1
	v_addc_co_u32_e32 v19, vcc, 0, v13, vcc
	v_mul_f32_e32 v19, 0xbfb8aa3b, v20
	v_exp_f32_e32 v19, v19
	v_lshlrev_b32_e32 v18, 16, v177
	v_add_f32_e32 v19, 1.0, v19
	v_rcp_f32_e32 v19, v19
	v_mul_f32_e32 v18, 0xbfb8aa3b, v18
	v_exp_f32_e32 v18, v18
	v_mul_f32_e32 v75, v19, v20
	v_add_co_u32_e32 v20, vcc, s0, v14
	s_mov_b32 s0, 0x17000
	s_nop 0
	v_addc_co_u32_e32 v21, vcc, 0, v15, vcc
	v_add_co_u32_e32 v20, vcc, s37, v12
	v_add_f32_e32 v18, 1.0, v18
	s_nop 0
	v_addc_co_u32_e32 v21, vcc, 0, v13, vcc
	v_rcp_f32_e32 v18, v18
	v_lshlrev_b32_e32 v22, 16, v146
	v_mul_f32_e32 v20, 0xbfb8aa3b, v22
	v_exp_f32_e32 v20, v20
	v_lshlrev_b32_e32 v19, 16, v178
	v_add_f32_e32 v20, 1.0, v20
	v_rcp_f32_e32 v20, v20
	v_mul_f32_e32 v19, 0xbfb8aa3b, v19
	v_exp_f32_e32 v19, v19
	v_mul_f32_e32 v77, v20, v22
	v_add_co_u32_e32 v20, vcc, s0, v14
	s_mov_b32 s0, 0x1b000
	s_nop 0
	v_addc_co_u32_e32 v21, vcc, 0, v15, vcc
	v_add_f32_e32 v19, 1.0, v19
	v_rcp_f32_e32 v19, v19
	v_lshlrev_b32_e32 v23, 16, v147
	v_add_co_u32_e32 v20, vcc, s74, v12
	s_nop 1
	v_addc_co_u32_e32 v21, vcc, 0, v13, vcc
	v_lshlrev_b32_e32 v20, 16, v179
	v_mul_f32_e32 v20, 0xbfb8aa3b, v20
	v_exp_f32_e32 v20, v20
	s_nop 0
	v_add_f32_e32 v20, 1.0, v20
	v_rcp_f32_e32 v22, v20
	v_mul_f32_e32 v20, 0xbfb8aa3b, v23
	v_exp_f32_e32 v20, v20
	s_nop 0
	v_add_f32_e32 v20, 1.0, v20
	v_rcp_f32_e32 v20, v20
	s_nop 0
	v_mul_f32_e32 v91, v20, v23
	v_add_co_u32_e32 v20, vcc, s0, v14
	s_mov_b32 s0, 0x25000
	s_nop 0
	v_addc_co_u32_e32 v21, vcc, 0, v15, vcc
	v_lshlrev_b32_e32 v26, 16, v148
	v_add_co_u32_e32 v20, vcc, s5, v12
	s_nop 1
	v_addc_co_u32_e32 v21, vcc, 0, v13, vcc
	v_lshlrev_b32_e32 v20, 16, v180
	v_mul_f32_e32 v20, 0xbfb8aa3b, v20
	v_exp_f32_e32 v20, v20
	s_nop 0
	v_add_f32_e32 v20, 1.0, v20
	v_rcp_f32_e32 v23, v20
	v_mul_f32_e32 v20, 0xbfb8aa3b, v26
	v_exp_f32_e32 v20, v20
	s_nop 0
	v_add_f32_e32 v20, 1.0, v20
	v_rcp_f32_e32 v20, v20
	s_nop 0
	v_mul_f32_e32 v99, v20, v26
	v_add_co_u32_e32 v20, vcc, s89, v14
	s_nop 1
	v_addc_co_u32_e32 v21, vcc, 0, v15, vcc
	v_lshlrev_b32_e32 v26, 16, v149
	v_add_co_u32_e32 v20, vcc, s89, v12
	s_nop 1
	v_addc_co_u32_e32 v21, vcc, 0, v13, vcc
	v_mul_f32_e32 v21, 0xbfb8aa3b, v26
; DI float bf2f(unsigned v) { return __uint_as_float(v << 16); }
; DI float flog(float x) { return __builtin_amdgcn_logf(x) * 0.6931471805599453f; }
; DI float sigm(float x) { return frcp(1.f + fexp(-x)); }
; DI float silu(float x) { return x * sigm(x); }
; DI void hgrn_prep_job(const Frame& F, int job, int layer, LAS unsigned char* scr) {
;     ...
; #pragma unroll
;         for (int t = 0; t < 32; ++t) {
;             const float qx = bf2f(qe[t]), fx = bf2f(fe[t]);
;             const float f = lb + (1.f - lb) * sigm(fx);
;             bsum += flog(f); bq[t] = bsum; kv[t] = 1.f - f; qv[t] = silu(qx);
;         }
	v_exp_f32_e32 v21, v21
	v_lshlrev_b32_e32 v20, 16, v181
	v_add_f32_e32 v21, 1.0, v21
	v_rcp_f32_e32 v21, v21
	v_mul_f32_e32 v20, 0xbfb8aa3b, v20
	v_exp_f32_e32 v20, v20
	v_mul_f32_e32 v95, v21, v26
	v_add_co_u32_e32 v26, vcc, s16, v14
	v_add_f32_e32 v20, 1.0, v20
	s_nop 0
	v_addc_co_u32_e32 v27, vcc, 0, v15, vcc
	v_add_co_u32_e32 v26, vcc, s17, v12
	v_rcp_f32_e32 v20, v20
	s_nop 0
	v_addc_co_u32_e32 v27, vcc, 0, v13, vcc
	v_lshlrev_b32_e32 v28, 16, v150
	v_mul_f32_e32 v26, 0xbfb8aa3b, v28
	v_exp_f32_e32 v26, v26
	v_lshlrev_b32_e32 v21, 16, v182
	v_add_f32_e32 v26, 1.0, v26
	v_rcp_f32_e32 v26, v26
	v_mul_f32_e32 v21, 0xbfb8aa3b, v21
	v_exp_f32_e32 v21, v21
	v_mul_f32_e32 v98, v26, v28
	v_add_co_u32_e32 v26, vcc, s6, v14
	v_add_f32_e32 v21, 1.0, v21
	s_nop 0
	v_addc_co_u32_e32 v27, vcc, 0, v15, vcc
	v_rcp_f32_e32 v21, v21
	v_lshlrev_b32_e32 v29, 16, v151
	v_add_co_u32_e32 v26, vcc, s0, v12
	s_mov_b32 s0, 0x2a000
	s_nop 0
	v_addc_co_u32_e32 v27, vcc, 0, v13, vcc
	v_lshlrev_b32_e32 v26, 16, v183
	v_mul_f32_e32 v26, 0xbfb8aa3b, v26
	v_exp_f32_e32 v26, v26
	s_nop 0
	v_add_f32_e32 v26, 1.0, v26
	v_rcp_f32_e32 v28, v26
	v_mul_f32_e32 v26, 0xbfb8aa3b, v29
	v_exp_f32_e32 v26, v26
	s_nop 0
	v_add_f32_e32 v26, 1.0, v26
	v_rcp_f32_e32 v26, v26
	s_nop 0
	v_mul_f32_e32 v101, v26, v29
	v_add_co_u32_e32 v26, vcc, s0, v14
	s_mov_b32 s0, 0x31000
	s_nop 0
	v_addc_co_u32_e32 v27, vcc, 0, v15, vcc
	v_lshlrev_b32_e32 v30, 16, v152
	v_add_co_u32_e32 v26, vcc, s18, v12
	s_nop 1
	v_addc_co_u32_e32 v27, vcc, 0, v13, vcc
	v_lshlrev_b32_e32 v26, 16, v186
	v_mul_f32_e32 v26, 0xbfb8aa3b, v26
	v_exp_f32_e32 v26, v26
	s_nop 0
	v_add_f32_e32 v26, 1.0, v26
	v_rcp_f32_e32 v29, v26
	v_mul_f32_e32 v26, 0xbfb8aa3b, v30
	v_exp_f32_e32 v26, v26
	s_nop 0
	v_add_f32_e32 v26, 1.0, v26
	v_rcp_f32_e32 v26, v26
	s_nop 0
	v_mul_f32_e32 v103, v26, v30
	v_add_co_u32_e32 v26, vcc, s9, v14
	s_nop 1
	v_addc_co_u32_e32 v27, vcc, 0, v15, vcc
	v_lshlrev_b32_e32 v30, 16, v153
	v_add_co_u32_e32 v26, vcc, s9, v12
	s_nop 1
	v_addc_co_u32_e32 v27, vcc, 0, v13, vcc
	v_mul_f32_e32 v27, 0xbfb8aa3b, v30
	v_exp_f32_e32 v27, v27
	v_lshlrev_b32_e32 v26, 16, v187
	v_add_f32_e32 v27, 1.0, v27
	v_rcp_f32_e32 v27, v27
	v_mul_f32_e32 v26, 0xbfb8aa3b, v26
	v_exp_f32_e32 v26, v26
	v_mul_f32_e32 v102, v27, v30
	v_add_co_u32_e32 v30, vcc, s0, v14
	s_mov_b32 s0, 0x35000
	s_nop 0
	v_addc_co_u32_e32 v31, vcc, 0, v15, vcc
	v_add_co_u32_e32 v30, vcc, s96, v12
	v_add_f32_e32 v26, 1.0, v26
	s_nop 0
	v_addc_co_u32_e32 v31, vcc, 0, v13, vcc
	v_rcp_f32_e32 v26, v26
	v_lshlrev_b32_e32 v32, 16, v154
	v_mul_f32_e32 v30, 0xbfb8aa3b, v32
	v_exp_f32_e32 v30, v30
	v_lshlrev_b32_e32 v27, 16, v188
	v_add_f32_e32 v30, 1.0, v30
	v_rcp_f32_e32 v30, v30
	v_mul_f32_e32 v27, 0xbfb8aa3b, v27
	v_exp_f32_e32 v27, v27
	v_mul_f32_e32 v104, v30, v32
	v_add_co_u32_e32 v30, vcc, s0, v14
	s_mov_b32 s0, 0x34000
	s_nop 0
	v_addc_co_u32_e32 v31, vcc, 0, v15, vcc
	v_add_f32_e32 v27, 1.0, v27
	v_rcp_f32_e32 v27, v27
	v_lshlrev_b32_e32 v32, 16, v155
	v_add_co_u32_e32 v30, vcc, s0, v12
	s_mov_b32 s0, 0x39000
	s_nop 0
	v_addc_co_u32_e32 v31, vcc, 0, v13, vcc
	v_mul_f32_e32 v31, 0xbfb8aa3b, v32
	v_exp_f32_e32 v31, v31
	v_lshlrev_b32_e32 v30, 16, v189
	v_add_f32_e32 v31, 1.0, v31
	v_rcp_f32_e32 v31, v31
	v_mul_f32_e32 v30, 0xbfb8aa3b, v30
	v_exp_f32_e32 v30, v30
	v_mul_f32_e32 v105, v31, v32
	v_add_co_u32_e32 v32, vcc, s0, v14
	s_mov_b32 s0, 0x40000
	s_nop 0
	v_addc_co_u32_e32 v33, vcc, 0, v15, vcc
	v_add_co_u32_e32 v32, vcc, s19, v12
	v_add_f32_e32 v30, 1.0, v30
	s_nop 0
	v_addc_co_u32_e32 v33, vcc, 0, v13, vcc
	v_rcp_f32_e32 v30, v30
	v_lshlrev_b32_e32 v34, 16, v156
	v_mul_f32_e32 v32, 0xbfb8aa3b, v34
	v_exp_f32_e32 v32, v32
	v_lshlrev_b32_e32 v31, 16, v190
	v_add_f32_e32 v32, 1.0, v32
	v_rcp_f32_e32 v32, v32
	v_mul_f32_e32 v31, 0xbfb8aa3b, v31
	v_exp_f32_e32 v31, v31
	v_mul_f32_e32 v106, v32, v34
	v_add_co_u32_e32 v32, vcc, s10, v14
	v_add_f32_e32 v31, 1.0, v31
	s_nop 0
	v_addc_co_u32_e32 v33, vcc, 0, v15, vcc
	v_rcp_f32_e32 v31, v31
	v_lshlrev_b32_e32 v34, 16, v157
	v_add_co_u32_e32 v32, vcc, s10, v12
	s_nop 1
	v_addc_co_u32_e32 v33, vcc, 0, v13, vcc
	v_mul_f32_e32 v33, 0xbfb8aa3b, v34
	v_exp_f32_e32 v33, v33
	v_lshlrev_b32_e32 v32, 16, v191
	v_add_f32_e32 v33, 1.0, v33
	v_rcp_f32_e32 v33, v33
	v_mul_f32_e32 v32, 0xbfb8aa3b, v32
	v_exp_f32_e32 v32, v32
	v_mul_f32_e32 v107, v33, v34
	v_add_co_u32_e32 v34, vcc, s0, v14
	s_mov_b32 s0, 0x44000
	s_nop 0
	v_addc_co_u32_e32 v35, vcc, 0, v15, vcc
	v_add_co_u32_e32 v34, vcc, s20, v12
	v_add_f32_e32 v32, 1.0, v32
	s_nop 0
	v_addc_co_u32_e32 v35, vcc, 0, v13, vcc
	v_rcp_f32_e32 v32, v32
	v_lshlrev_b32_e32 v36, 16, v158
	v_mul_f32_e32 v34, 0xbfb8aa3b, v36
	v_exp_f32_e32 v34, v34
	v_lshlrev_b32_e32 v33, 16, v192
	v_add_f32_e32 v34, 1.0, v34
	v_rcp_f32_e32 v34, v34
	v_mul_f32_e32 v33, 0xbfb8aa3b, v33
	v_exp_f32_e32 v33, v33
	v_mul_f32_e32 v108, v34, v36
	v_add_co_u32_e32 v34, vcc, s0, v14
	s_mov_b32 s0, 0x43000
	s_nop 0
	v_addc_co_u32_e32 v35, vcc, 0, v15, vcc
	v_add_f32_e32 v33, 1.0, v33
	v_rcp_f32_e32 v33, v33
	v_lshlrev_b32_e32 v37, 16, v159
	v_add_co_u32_e32 v34, vcc, s0, v12
	s_mov_b32 s0, 0x48000
	s_nop 0
	v_addc_co_u32_e32 v35, vcc, 0, v13, vcc
	v_lshlrev_b32_e32 v34, 16, v193
	v_mul_f32_e32 v34, 0xbfb8aa3b, v34
	v_exp_f32_e32 v34, v34
	s_nop 0
	v_add_f32_e32 v34, 1.0, v34
	v_rcp_f32_e32 v36, v34
	v_mul_f32_e32 v34, 0xbfb8aa3b, v37
	v_exp_f32_e32 v34, v34
	s_nop 0
	v_add_f32_e32 v34, 1.0, v34
	v_rcp_f32_e32 v34, v34
	s_nop 0
	v_mul_f32_e32 v109, v34, v37
	v_add_co_u32_e32 v34, vcc, s0, v14
	s_mov_b32 s0, 0x4f000
	s_nop 0
	v_addc_co_u32_e32 v35, vcc, 0, v15, vcc
	v_lshlrev_b32_e32 v38, 16, v160
; DI float bf2f(unsigned v) { return __uint_as_float(v << 16); }
; DI float flog(float x) { return __builtin_amdgcn_logf(x) * 0.6931471805599453f; }
; DI float sigm(float x) { return frcp(1.f + fexp(-x)); }
; DI float silu(float x) { return x * sigm(x); }
; DI void hgrn_prep_job(const Frame& F, int job, int layer, LAS unsigned char* scr) {
;     ...
; #pragma unroll
;         for (int t = 0; t < 32; ++t) {
;             const float qx = bf2f(qe[t]), fx = bf2f(fe[t]);
;             const float f = lb + (1.f - lb) * sigm(fx);
;             bsum += flog(f); bq[t] = bsum; kv[t] = 1.f - f; qv[t] = silu(qx);
;         }
	v_add_co_u32_e32 v34, vcc, s21, v12
	s_nop 1
	v_addc_co_u32_e32 v35, vcc, 0, v13, vcc
	v_lshlrev_b32_e32 v34, 16, v194
	v_mul_f32_e32 v34, 0xbfb8aa3b, v34
	v_exp_f32_e32 v34, v34
	s_nop 0
	v_add_f32_e32 v34, 1.0, v34
	v_rcp_f32_e32 v37, v34
	v_mul_f32_e32 v34, 0xbfb8aa3b, v38
	v_exp_f32_e32 v34, v34
	s_nop 0
	v_add_f32_e32 v34, 1.0, v34
	v_rcp_f32_e32 v34, v34
	s_nop 0
	v_mul_f32_e32 v110, v34, v38
	v_add_co_u32_e32 v34, vcc, s11, v14
	s_nop 1
	v_addc_co_u32_e32 v35, vcc, 0, v15, vcc
	v_lshlrev_b32_e32 v38, 16, v161
	v_add_co_u32_e32 v34, vcc, s11, v12
	s_nop 1
	v_addc_co_u32_e32 v35, vcc, 0, v13, vcc
	v_mul_f32_e32 v35, 0xbfb8aa3b, v38
	v_exp_f32_e32 v35, v35
	v_lshlrev_b32_e32 v34, 16, v195
	v_add_f32_e32 v35, 1.0, v35
	v_rcp_f32_e32 v35, v35
	v_mul_f32_e32 v34, 0xbfb8aa3b, v34
	v_exp_f32_e32 v34, v34
	v_mul_f32_e32 v111, v35, v38
	v_add_co_u32_e32 v38, vcc, s0, v14
	s_mov_b32 s0, 0x53000
	s_nop 0
	v_addc_co_u32_e32 v39, vcc, 0, v15, vcc
	v_add_co_u32_e32 v38, vcc, s22, v12
	v_add_f32_e32 v34, 1.0, v34
	s_nop 0
	v_addc_co_u32_e32 v39, vcc, 0, v13, vcc
	v_rcp_f32_e32 v34, v34
	v_lshlrev_b32_e32 v40, 16, v162
	v_mul_f32_e32 v38, 0xbfb8aa3b, v40
	v_exp_f32_e32 v38, v38
	v_lshlrev_b32_e32 v35, 16, v196
	v_add_f32_e32 v38, 1.0, v38
	v_rcp_f32_e32 v38, v38
	v_mul_f32_e32 v35, 0xbfb8aa3b, v35
	v_exp_f32_e32 v35, v35
	v_mul_f32_e32 v112, v38, v40
	v_add_co_u32_e32 v38, vcc, s0, v14
	s_mov_b32 s0, 0x52000
	s_nop 0
	v_addc_co_u32_e32 v39, vcc, 0, v15, vcc
	v_add_f32_e32 v35, 1.0, v35
	v_rcp_f32_e32 v35, v35
	v_lshlrev_b32_e32 v41, 16, v163
	v_add_co_u32_e32 v38, vcc, s0, v12
	s_mov_b32 s0, 0x57000
	s_nop 0
	v_addc_co_u32_e32 v39, vcc, 0, v13, vcc
	v_lshlrev_b32_e32 v38, 16, v197
	v_mul_f32_e32 v38, 0xbfb8aa3b, v38
	v_exp_f32_e32 v38, v38
	s_nop 0
	v_add_f32_e32 v38, 1.0, v38
	v_rcp_f32_e32 v40, v38
	v_mul_f32_e32 v38, 0xbfb8aa3b, v41
	v_exp_f32_e32 v38, v38
	s_nop 0
	v_add_f32_e32 v38, 1.0, v38
	v_rcp_f32_e32 v38, v38
	s_nop 0
	v_mul_f32_e32 v113, v38, v41
	v_add_co_u32_e32 v38, vcc, s0, v14
	s_mov_b32 s0, 0x5e000
	s_nop 0
	v_addc_co_u32_e32 v39, vcc, 0, v15, vcc
	v_lshlrev_b32_e32 v42, 16, v164
	v_add_co_u32_e32 v38, vcc, s23, v12
	s_nop 1
	v_addc_co_u32_e32 v39, vcc, 0, v13, vcc
	v_lshlrev_b32_e32 v38, 16, v198
	v_mul_f32_e32 v38, 0xbfb8aa3b, v38
	v_exp_f32_e32 v38, v38
	s_nop 0
	v_add_f32_e32 v38, 1.0, v38
	v_rcp_f32_e32 v41, v38
	v_mul_f32_e32 v38, 0xbfb8aa3b, v42
	v_exp_f32_e32 v38, v38
	s_nop 0
	v_add_f32_e32 v38, 1.0, v38
	v_rcp_f32_e32 v38, v38
	s_nop 0
	v_mul_f32_e32 v114, v38, v42
	v_add_co_u32_e32 v38, vcc, s12, v14
	s_nop 1
	v_addc_co_u32_e32 v39, vcc, 0, v15, vcc
	v_lshlrev_b32_e32 v42, 16, v165
	v_add_co_u32_e32 v38, vcc, s12, v12
	s_nop 1
	v_addc_co_u32_e32 v39, vcc, 0, v13, vcc
	v_mul_f32_e32 v39, 0xbfb8aa3b, v42
	v_exp_f32_e32 v39, v39
	v_lshlrev_b32_e32 v38, 16, v199
	v_add_f32_e32 v39, 1.0, v39
	v_rcp_f32_e32 v39, v39
	v_mul_f32_e32 v38, 0xbfb8aa3b, v38
	v_exp_f32_e32 v38, v38
	v_mul_f32_e32 v115, v39, v42
	v_add_co_u32_e32 v42, vcc, s0, v14
	s_mov_b32 s0, 0x62000
	s_nop 0
	v_addc_co_u32_e32 v43, vcc, 0, v15, vcc
	v_add_co_u32_e32 v42, vcc, s24, v12
	v_add_f32_e32 v38, 1.0, v38
	s_nop 0
	v_addc_co_u32_e32 v43, vcc, 0, v13, vcc
	v_rcp_f32_e32 v38, v38
	v_lshlrev_b32_e32 v44, 16, v166
	v_mul_f32_e32 v42, 0xbfb8aa3b, v44
	v_exp_f32_e32 v42, v42
	v_lshlrev_b32_e32 v39, 16, v200
	v_add_f32_e32 v42, 1.0, v42
	v_rcp_f32_e32 v42, v42
	v_mul_f32_e32 v39, 0xbfb8aa3b, v39
	v_exp_f32_e32 v39, v39
	v_mul_f32_e32 v116, v42, v44
	v_add_co_u32_e32 v42, vcc, s0, v14
	s_mov_b32 s0, 0x61000
	s_nop 0
	v_addc_co_u32_e32 v43, vcc, 0, v15, vcc
	v_add_f32_e32 v39, 1.0, v39
	v_rcp_f32_e32 v39, v39
	v_lshlrev_b32_e32 v45, 16, v167
	v_add_co_u32_e32 v42, vcc, s0, v12
	s_mov_b32 s0, 0x66000
	s_nop 0
	v_addc_co_u32_e32 v43, vcc, 0, v13, vcc
	v_lshlrev_b32_e32 v42, 16, v201
	v_mul_f32_e32 v42, 0xbfb8aa3b, v42
	v_exp_f32_e32 v42, v42
	s_nop 0
	v_add_f32_e32 v42, 1.0, v42
	v_rcp_f32_e32 v44, v42
	v_mul_f32_e32 v42, 0xbfb8aa3b, v45
	v_exp_f32_e32 v42, v42
	s_nop 0
	v_add_f32_e32 v42, 1.0, v42
	v_rcp_f32_e32 v42, v42
	s_nop 0
	v_mul_f32_e32 v118, v42, v45
	v_add_co_u32_e32 v42, vcc, s0, v14
	s_mov_b32 s0, 0x6d000
	s_nop 0
	v_addc_co_u32_e32 v43, vcc, 0, v15, vcc
	v_lshlrev_b32_e32 v46, 16, v168
	v_add_co_u32_e32 v42, vcc, s25, v12
	s_nop 1
	v_addc_co_u32_e32 v43, vcc, 0, v13, vcc
	v_lshlrev_b32_e32 v42, 16, v202
	v_mul_f32_e32 v42, 0xbfb8aa3b, v42
	v_exp_f32_e32 v42, v42
	s_nop 0
	v_add_f32_e32 v42, 1.0, v42
	v_rcp_f32_e32 v45, v42
	v_mul_f32_e32 v42, 0xbfb8aa3b, v46
	v_exp_f32_e32 v42, v42
	s_nop 0
	v_add_f32_e32 v42, 1.0, v42
	v_rcp_f32_e32 v42, v42
	s_nop 0
	v_mul_f32_e32 v121, v42, v46
	v_add_co_u32_e32 v42, vcc, s13, v14
	s_nop 1
	v_addc_co_u32_e32 v43, vcc, 0, v15, vcc
	v_lshlrev_b32_e32 v46, 16, v169
	v_add_co_u32_e32 v42, vcc, s13, v12
	s_nop 1
	v_addc_co_u32_e32 v43, vcc, 0, v13, vcc
	v_mul_f32_e32 v43, 0xbfb8aa3b, v46
	v_exp_f32_e32 v43, v43
	v_lshlrev_b32_e32 v42, 16, v203
	v_add_f32_e32 v43, 1.0, v43
	v_rcp_f32_e32 v43, v43
	v_mul_f32_e32 v42, 0xbfb8aa3b, v42
	v_exp_f32_e32 v42, v42
	v_mul_f32_e32 v122, v43, v46
	v_add_co_u32_e32 v46, vcc, s0, v14
	s_mov_b32 s0, 0x71000
	s_nop 0
	v_addc_co_u32_e32 v47, vcc, 0, v15, vcc
	v_add_co_u32_e32 v46, vcc, s26, v12
	v_add_f32_e32 v42, 1.0, v42
	s_nop 0
	v_addc_co_u32_e32 v47, vcc, 0, v13, vcc
	v_rcp_f32_e32 v42, v42
	v_lshlrev_b32_e32 v78, 16, v170
	v_mul_f32_e32 v46, 0xbfb8aa3b, v78
	v_exp_f32_e32 v46, v46
	v_lshlrev_b32_e32 v43, 16, v204
	v_add_f32_e32 v46, 1.0, v46
	v_rcp_f32_e32 v46, v46
	v_mul_f32_e32 v43, 0xbfb8aa3b, v43
	v_exp_f32_e32 v43, v43
	v_mul_f32_e32 v123, v46, v78
	v_add_co_u32_e32 v46, vcc, s0, v14
	s_mov_b32 s0, 0x70000
	s_nop 0
	v_addc_co_u32_e32 v47, vcc, 0, v15, vcc
	v_add_f32_e32 v43, 1.0, v43
	v_rcp_f32_e32 v43, v43
	v_lshlrev_b32_e32 v78, 16, v171
	v_add_co_u32_e32 v46, vcc, s0, v12
	s_mov_b32 s0, 0x75000
	s_nop 0
	v_addc_co_u32_e32 v47, vcc, 0, v13, vcc
	v_add_co_u32_e32 v14, vcc, s0, v14
	s_nop 0
	v_addc_co_u32_e32 v15, vcc, 0, v15, vcc
	v_add_co_u32_e32 v12, vcc, s27, v12
	s_nop 0
	v_addc_co_u32_e32 v13, vcc, 0, v13, vcc
	v_mul_f32_e32 v47, 0xbfb8aa3b, v78
	v_exp_f32_e32 v47, v47
	s_mov_b32 s0, 0x3f317218
	v_add_f32_e32 v47, 1.0, v47
	v_rcp_f32_e32 v47, v47
	s_waitcnt vmcnt(2)
; #define GAS __attribute__((address_space(1)))
; #define LAS __attribute__((address_space(3)))
; DI unsigned pk2(float lo, float hi) { f32x2 v = {lo, hi}; bf16x2_t b = __builtin_convertvector(v, bf16x2_t); return __builtin_bit_cast(unsigned, b); }
; DI float bf2f(unsigned v) { return __uint_as_float(v << 16); }
; DI float fexp(float x) { return __builtin_amdgcn_exp2f(x * 1.4426950408889634f); }
; DI float flog(float x) { return __builtin_amdgcn_logf(x) * 0.6931471805599453f; }
; DI float frcp(float x) { return __builtin_amdgcn_rcpf(x); }
; DI float sigm(float x) { return frcp(1.f + fexp(-x)); }
; DI float silu(float x) { return x * sigm(x); }
; DI void hgrn_prep_job(const Frame& F, int job, int layer, LAS unsigned char* scr) {
;     ...
;         for (int t = 0; t < 32; ++t) ve[t] = pv[(size_t)t * NP];
;     ...
;         for (int t = 0; t < 32; ++t) {
;             const float qx = bf2f(qe[t]), fx = bf2f(fe[t]);
;             const float f = lb + (1.f - lb) * sigm(fx);
;             bsum += flog(f); bq[t] = bsum; kv[t] = 1.f - f; qv[t] = silu(qx);
;         }
;         ((GAS float*)he)[dk] = fexp(bsum);
; #pragma unroll
;         for (int t = 0; t < 32; ++t) {
;             const float e = fexp(bq[t]);
;             *(LAS bf16*)(QL + t * 272 + dk * 2) = (bf16)(pk2(qv[t] * e, 0.f) & 0xffffu);
;             *(LAS bf16*)(KL + t * 272 + dk * 2) = (bf16)(pk2(kv[t] * frcp(e), 0.f) & 0xffffu);
;             kv[t] = kv[t] * fexp(bsum - bq[t]);
;         }
	v_lshlrev_b32_e32 v46, 16, v205
	v_mul_f32_e32 v117, v47, v78
	v_mul_f32_e32 v46, 0xbfb8aa3b, v46
	v_exp_f32_e32 v46, v46
	s_waitcnt vmcnt(1)
	v_lshlrev_b32_e32 v14, 16, v172
	v_add_f32_e32 v46, 1.0, v46
	v_lshlrev_b32_e32 v12, 16, v206
	v_mul_f32_e32 v12, 0xbfb8aa3b, v12
	v_exp_f32_e32 v12, v12
	v_rcp_f32_e32 v46, v46
	v_add_f32_e32 v12, 1.0, v12
	v_rcp_f32_e32 v47, v12
	v_mul_f32_e32 v12, 0xbfb8aa3b, v14
	v_exp_f32_e32 v12, v12
	s_nop 0
	v_add_f32_e32 v12, 1.0, v12
	v_rcp_f32_e32 v12, v12
	s_nop 0
	v_mul_f32_e32 v120, v12, v14
	v_pk_fma_f32 v[14:15], v[6:7], v[16:17], v[4:5] op_sel_hi:[0,1,0]
	v_log_f32_e32 v16, v14
	v_lshl_add_u64 v[12:13], s[64:65], 0, v[10:11]
	v_pk_fma_f32 v[10:11], v[6:7], v[36:37], v[4:5] op_sel_hi:[0,1,0]
	v_log_f32_e32 v124, v10
	v_fma_f32 v128, v16, s0, 0
	v_log_f32_e32 v16, v15
	v_log_f32_e32 v125, v11
	v_pk_add_f32 v[36:37], v[10:11], 1.0 op_sel_hi:[1,0] neg_lo:[1,0] neg_hi:[1,0]
	v_pk_fma_f32 v[10:11], v[6:7], v[32:33], v[4:5] op_sel_hi:[0,1,0]
	v_fmamk_f32 v129, v16, 0x3f317218, v128
	v_mul_f32_e32 v16, 0x3fb8aa3b, v128
	v_exp_f32_e32 v130, v16
	v_add_co_u32_e32 v16, vcc, s14, v8
	v_log_f32_e32 v126, v10
	s_nop 0
	v_addc_co_u32_e32 v17, vcc, 0, v9, vcc
	global_load_ushort v78, v[16:17], off offset:3072
	v_add_co_u32_e32 v16, vcc, s15, v8
	v_log_f32_e32 v127, v11
	s_nop 0
	v_addc_co_u32_e32 v17, vcc, 0, v9, vcc
	global_load_ushort v79, v[16:17], off offset:1024
	v_add_co_u32_e32 v16, vcc, s20, v8
	v_pk_add_f32 v[32:33], v[10:11], 1.0 op_sel_hi:[1,0] neg_lo:[1,0] neg_hi:[1,0]
	s_nop 0
	v_addc_co_u32_e32 v17, vcc, 0, v9, vcc
	v_pk_fma_f32 v[10:11], v[6:7], v[24:25], v[4:5] op_sel_hi:[0,1,0]
	v_mul_f32_e32 v7, v7, v130
	global_load_ushort v80, v[16:17], off offset:3072
	v_add_co_u32_e32 v16, vcc, s21, v8
	v_cvt_pk_bf16_f32 v7, v7, s0
	s_nop 0
	v_addc_co_u32_e32 v17, vcc, 0, v9, vcc
	global_load_ushort v81, v[16:17], off offset:1024
	v_add_co_u32_e32 v16, vcc, s37, v8
	ds_write_b16 v119, v7
	v_rcp_f32_e32 v7, v130
	v_addc_co_u32_e32 v17, vcc, 0, v9, vcc
	global_load_ushort v82, v[16:17], off offset:3072
	v_add_co_u32_e32 v16, vcc, s5, v8
	v_pk_add_f32 v[14:15], v[14:15], 1.0 op_sel_hi:[1,0] neg_lo:[1,0] neg_hi:[1,0]
	s_nop 0
	v_addc_co_u32_e32 v17, vcc, 0, v9, vcc
	global_load_ushort v83, v[16:17], off offset:1024
	v_add_co_u32_e32 v16, vcc, s22, v8
	v_mul_f32_e32 v7, v14, v7
	s_nop 0
	v_addc_co_u32_e32 v17, vcc, 0, v9, vcc
	v_cvt_pk_bf16_f32 v7, v7, s0
	global_load_ushort v84, v[16:17], off offset:3072
	v_add_co_u32_e32 v16, vcc, s23, v8
	ds_write_b16 v119, v7 offset:8704
	v_mul_f32_e32 v7, 0x3fb8aa3b, v129
	v_addc_co_u32_e32 v17, vcc, 0, v9, vcc
	v_exp_f32_e32 v7, v7
	global_load_ushort v85, v[16:17], off offset:1024
	v_add_co_u32_e32 v16, vcc, s17, v8
	v_mul_f32_e32 v5, v5, v7
	s_nop 0
	v_addc_co_u32_e32 v17, vcc, 0, v9, vcc
	global_load_ushort v86, v[16:17], off offset:3072
	v_add_co_u32_e32 v16, vcc, s18, v8
	v_cvt_pk_bf16_f32 v5, v5, s0
	s_nop 0
	v_addc_co_u32_e32 v17, vcc, 0, v9, vcc
	global_load_ushort v87, v[16:17], off offset:1024
	v_add_co_u32_e32 v16, vcc, s24, v8
	ds_write_b16 v119, v5 offset:272
	s_nop 0
	v_addc_co_u32_e32 v17, vcc, 0, v9, vcc
	v_rcp_f32_e32 v5, v7
	v_log_f32_e32 v24, v10
	global_load_ushort v88, v[16:17], off offset:3072
	v_add_co_u32_e32 v16, vcc, s25, v8
	v_mul_f32_e32 v5, v15, v5
	s_nop 0
	v_addc_co_u32_e32 v17, vcc, 0, v9, vcc
	global_load_ushort v89, v[16:17], off offset:1024
	v_add_co_u32_e32 v16, vcc, s96, v8
	v_cvt_pk_bf16_f32 v5, v5, s0
	s_nop 0
	v_addc_co_u32_e32 v17, vcc, 0, v9, vcc
	global_load_ushort v90, v[16:17], off offset:3072
	v_add_co_u32_e32 v16, vcc, s19, v8
	v_fmamk_f32 v7, v24, 0x3f317218, v129
	s_nop 0
	v_addc_co_u32_e32 v17, vcc, 0, v9, vcc
	ds_write_b16 v119, v5 offset:8976
	v_mul_f32_e32 v5, 0x3fb8aa3b, v7
	global_load_ushort v92, v[16:17], off offset:1024
	v_add_co_u32_e32 v16, vcc, s26, v8
	v_exp_f32_e32 v5, v5
	s_nop 0
	v_addc_co_u32_e32 v17, vcc, 0, v9, vcc
	v_add_co_u32_e32 v8, vcc, s27, v8
	global_load_ushort v93, v[16:17], off offset:3072
	s_nop 0
	v_addc_co_u32_e32 v9, vcc, 0, v9, vcc
	global_load_ushort v94, v[8:9], off offset:1024
	s_waitcnt vmcnt(0)
	v_mul_f32_e32 v8, v74, v5
	v_rcp_f32_e32 v5, v5
	v_log_f32_e32 v25, v11
	v_pk_add_f32 v[10:11], v[10:11], 1.0 op_sel_hi:[1,0] neg_lo:[1,0] neg_hi:[1,0]
	v_cvt_pk_bf16_f32 v8, v8, s0
	v_mul_f32_e32 v5, v10, v5
	v_fmamk_f32 v130, v25, 0x3f317218, v7
	v_cvt_pk_bf16_f32 v5, v5, s0
	ds_write_b16 v119, v5 offset:9248
	v_mul_f32_e32 v5, 0x3fb8aa3b, v130
	v_exp_f32_e32 v5, v5
	ds_write_b16 v119, v8 offset:544
	s_and_b64 vcc, exec, s[82:83]
	s_mov_b64 s[82:83], 0
	v_mul_f32_e32 v8, v76, v5
	v_rcp_f32_e32 v5, v5
	v_cvt_pk_bf16_f32 v8, v8, s0
	ds_write_b16 v119, v8 offset:816
	v_mul_f32_e32 v5, v11, v5
	v_cvt_pk_bf16_f32 v5, v5, s0
	v_pk_fma_f32 v[8:9], v[6:7], v[40:41], v[4:5] op_sel_hi:[0,1,0]
	v_log_f32_e32 v74, v8
	v_log_f32_e32 v76, v9
	v_pk_add_f32 v[40:41], v[8:9], 1.0 op_sel_hi:[1,0] neg_lo:[1,0] neg_hi:[1,0]
	v_pk_fma_f32 v[8:9], v[6:7], v[34:35], v[4:5] op_sel_hi:[0,1,0]
	v_log_f32_e32 v131, v8
	v_log_f32_e32 v132, v9
	v_pk_add_f32 v[24:25], v[8:9], 1.0 op_sel_hi:[1,0] neg_lo:[1,0] neg_hi:[1,0]
	v_pk_fma_f32 v[8:9], v[6:7], v[22:23], v[4:5] op_sel_hi:[0,1,0]
	ds_write_b16 v119, v5 offset:9520
	v_log_f32_e32 v5, v8
	v_log_f32_e32 v22, v9
	v_pk_add_f32 v[16:17], v[8:9], 1.0 op_sel_hi:[1,0] neg_lo:[1,0] neg_hi:[1,0]
	v_pk_fma_f32 v[8:9], v[6:7], v[18:19], v[4:5] op_sel_hi:[0,1,0]
	v_log_f32_e32 v18, v8
	v_log_f32_e32 v19, v9
	v_pk_add_f32 v[8:9], v[8:9], 1.0 op_sel_hi:[1,0] neg_lo:[1,0] neg_hi:[1,0]
	v_fmamk_f32 v133, v18, 0x3f317218, v130
	v_mul_f32_e32 v18, 0x3fb8aa3b, v133
	v_exp_f32_e32 v18, v18
; #define GAS __attribute__((address_space(1)))
; #define LAS __attribute__((address_space(3)))
; DI unsigned pk2(float lo, float hi) { f32x2 v = {lo, hi}; bf16x2_t b = __builtin_convertvector(v, bf16x2_t); return __builtin_bit_cast(unsigned, b); }
; DI float bf2f(unsigned v) { return __uint_as_float(v << 16); }
; DI float fexp(float x) { return __builtin_amdgcn_exp2f(x * 1.4426950408889634f); }
; DI float flog(float x) { return __builtin_amdgcn_logf(x) * 0.6931471805599453f; }
; DI float frcp(float x) { return __builtin_amdgcn_rcpf(x); }
; DI float sigm(float x) { return frcp(1.f + fexp(-x)); }
; DI float silu(float x) { return x * sigm(x); }
; DI void hgrn_prep_job(const Frame& F, int job, int layer, LAS unsigned char* scr) {
;     ...
;         for (int t = 0; t < 32; ++t) {
;             const float qx = bf2f(qe[t]), fx = bf2f(fe[t]);
;             const float f = lb + (1.f - lb) * sigm(fx);
;             bsum += flog(f); bq[t] = bsum; kv[t] = 1.f - f; qv[t] = silu(qx);
;         }
;         ((GAS float*)he)[dk] = fexp(bsum);
; #pragma unroll
;         for (int t = 0; t < 32; ++t) {
;             const float e = fexp(bq[t]);
;             *(LAS bf16*)(QL + t * 272 + dk * 2) = (bf16)(pk2(qv[t] * e, 0.f) & 0xffffu);
;             *(LAS bf16*)(KL + t * 272 + dk * 2) = (bf16)(pk2(kv[t] * frcp(e), 0.f) & 0xffffu);
;             kv[t] = kv[t] * fexp(bsum - bq[t]);
;         }
	v_fmamk_f32 v134, v19, 0x3f317218, v133
	v_mul_f32_e32 v19, v75, v18
	v_rcp_f32_e32 v18, v18
	v_cvt_pk_bf16_f32 v19, v19, s0
	ds_write_b16 v119, v19 offset:1088
	v_fmamk_f32 v75, v5, 0x3f317218, v134
	v_mul_f32_e32 v18, v8, v18
	v_cvt_pk_bf16_f32 v18, v18, s0
	ds_write_b16 v119, v18 offset:9792
	v_mul_f32_e32 v18, 0x3fb8aa3b, v134
	v_exp_f32_e32 v18, v18
	v_mul_f32_e32 v5, 0x3fb8aa3b, v75
	v_exp_f32_e32 v5, v5
	v_mul_f32_e32 v19, v77, v18
	v_rcp_f32_e32 v18, v18
	v_fmamk_f32 v77, v22, 0x3f317218, v75
	v_cvt_pk_bf16_f32 v19, v19, s0
	ds_write_b16 v119, v19 offset:1360
	v_mul_f32_e32 v18, v9, v18
	v_cvt_pk_bf16_f32 v18, v18, s0
	ds_write_b16 v119, v18 offset:10064
	v_mul_f32_e32 v18, v91, v5
	v_rcp_f32_e32 v5, v5
	v_cvt_pk_bf16_f32 v18, v18, s0
	ds_write_b16 v119, v18 offset:1632
	v_mul_f32_e32 v5, v16, v5
	v_cvt_pk_bf16_f32 v5, v5, s0
	ds_write_b16 v119, v5 offset:10336
	v_mul_f32_e32 v5, 0x3fb8aa3b, v77
	v_exp_f32_e32 v5, v5
	s_nop 0
	v_mul_f32_e32 v18, v99, v5
	v_rcp_f32_e32 v5, v5
	v_cvt_pk_bf16_f32 v18, v18, s0
	ds_write_b16 v119, v18 offset:1904
	v_mul_f32_e32 v5, v17, v5
	v_cvt_pk_bf16_f32 v5, v5, s0
	v_pk_fma_f32 v[18:19], v[6:7], v[44:45], v[4:5] op_sel_hi:[0,1,0]
	v_log_f32_e32 v91, v18
	v_log_f32_e32 v99, v19
	v_pk_add_f32 v[34:35], v[18:19], 1.0 op_sel_hi:[1,0] neg_lo:[1,0] neg_hi:[1,0]
	v_pk_fma_f32 v[18:19], v[6:7], v[38:39], v[4:5] op_sel_hi:[0,1,0]
	v_log_f32_e32 v135, v18
	v_log_f32_e32 v136, v19
	v_pk_add_f32 v[38:39], v[18:19], 1.0 op_sel_hi:[1,0] neg_lo:[1,0] neg_hi:[1,0]
	v_pk_fma_f32 v[18:19], v[6:7], v[28:29], v[4:5] op_sel_hi:[0,1,0]
	ds_write_b16 v119, v5 offset:10608
	v_log_f32_e32 v5, v18
	v_log_f32_e32 v22, v19
	v_pk_add_f32 v[18:19], v[18:19], 1.0 op_sel_hi:[1,0] neg_lo:[1,0] neg_hi:[1,0]
	v_pk_fma_f32 v[20:21], v[6:7], v[20:21], v[4:5] op_sel_hi:[0,1,0]
	v_log_f32_e32 v23, v20
	v_log_f32_e32 v28, v21
	v_pk_add_f32 v[20:21], v[20:21], 1.0 op_sel_hi:[1,0] neg_lo:[1,0] neg_hi:[1,0]
	v_fmamk_f32 v29, v23, 0x3f317218, v77
	v_mul_f32_e32 v23, 0x3fb8aa3b, v29
	v_exp_f32_e32 v23, v23
	v_fmamk_f32 v28, v28, 0x3f317218, v29
	v_mul_f32_e32 v44, v95, v23
	v_rcp_f32_e32 v23, v23
	v_fmamk_f32 v95, v5, 0x3f317218, v28
	v_mul_f32_e32 v5, 0x3fb8aa3b, v95
	v_exp_f32_e32 v5, v5
	v_mul_f32_e32 v23, v20, v23
	v_cvt_pk_bf16_f32 v23, v23, s0
	ds_write_b16 v119, v23 offset:10880
	v_mul_f32_e32 v23, 0x3fb8aa3b, v28
	v_exp_f32_e32 v23, v23
	v_cvt_pk_bf16_f32 v44, v44, s0
	ds_write_b16 v119, v44 offset:2176
	v_mul_f32_e32 v44, v98, v23
	v_fmamk_f32 v98, v22, 0x3f317218, v95
	v_mul_f32_e32 v22, v101, v5
	v_rcp_f32_e32 v5, v5
	v_cvt_pk_bf16_f32 v22, v22, s0
	v_rcp_f32_e32 v23, v23
	ds_write_b16 v119, v22 offset:2720
	v_mul_f32_e32 v5, v18, v5
	v_cvt_pk_bf16_f32 v5, v5, s0
	ds_write_b16 v119, v5 offset:11424
	v_mul_f32_e32 v5, 0x3fb8aa3b, v98
	v_exp_f32_e32 v5, v5
	v_mul_f32_e32 v23, v21, v23
	v_cvt_pk_bf16_f32 v23, v23, s0
	v_cvt_pk_bf16_f32 v44, v44, s0
	v_mul_f32_e32 v22, v103, v5
	v_rcp_f32_e32 v5, v5
	v_cvt_pk_bf16_f32 v22, v22, s0
	ds_write_b16 v119, v23 offset:11152
	ds_write_b16 v119, v22 offset:2992
	v_mul_f32_e32 v5, v19, v5
	v_cvt_pk_bf16_f32 v5, v5, s0
	v_pk_fma_f32 v[22:23], v[6:7], v[46:47], v[4:5] op_sel_hi:[0,1,0]
	ds_write_b16 v119, v44 offset:2448
	v_log_f32_e32 v46, v22
	v_log_f32_e32 v47, v23
	v_pk_add_f32 v[44:45], v[22:23], 1.0 op_sel_hi:[1,0] neg_lo:[1,0] neg_hi:[1,0]
	v_pk_fma_f32 v[22:23], v[6:7], v[42:43], v[4:5] op_sel_hi:[0,1,0]
	ds_write_b16 v119, v5 offset:11696
	v_log_f32_e32 v101, v22
	v_log_f32_e32 v103, v23
	v_pk_add_f32 v[42:43], v[22:23], 1.0 op_sel_hi:[1,0] neg_lo:[1,0] neg_hi:[1,0]
	v_pk_fma_f32 v[22:23], v[6:7], v[30:31], v[4:5] op_sel_hi:[0,1,0]
	v_pk_fma_f32 v[4:5], v[6:7], v[26:27], v[4:5] op_sel_hi:[0,1,0]
	v_log_f32_e32 v6, v4
	v_pk_add_f32 v[26:27], v[4:5], 1.0 op_sel_hi:[1,0] neg_lo:[1,0] neg_hi:[1,0]
	v_log_f32_e32 v137, v5
	v_log_f32_e32 v30, v22
	v_fmamk_f32 v138, v6, 0x3f317218, v98
	v_mul_f32_e32 v4, 0x3fb8aa3b, v138
	v_exp_f32_e32 v4, v4
	v_fmamk_f32 v137, v137, 0x3f317218, v138
	v_fmamk_f32 v30, v30, 0x3f317218, v137
	v_log_f32_e32 v31, v23
	v_mul_f32_e32 v5, v102, v4
	v_rcp_f32_e32 v4, v4
	v_cvt_pk_bf16_f32 v5, v5, s0
	ds_write_b16 v119, v5 offset:3264
	v_pk_add_f32 v[22:23], v[22:23], 1.0 op_sel_hi:[1,0] neg_lo:[1,0] neg_hi:[1,0]
	v_mul_f32_e32 v4, v26, v4
	v_cvt_pk_bf16_f32 v4, v4, s0
	ds_write_b16 v119, v4 offset:11968
	v_mul_f32_e32 v4, 0x3fb8aa3b, v137
	v_exp_f32_e32 v4, v4
	v_fmamk_f32 v31, v31, 0x3f317218, v30
	v_fmamk_f32 v102, v126, 0x3f317218, v31
	v_mul_f32_e32 v5, v104, v4
	v_rcp_f32_e32 v4, v4
	v_cvt_pk_bf16_f32 v5, v5, s0
	ds_write_b16 v119, v5 offset:3536
	v_fmamk_f32 v104, v127, 0x3f317218, v102
	v_mul_f32_e32 v4, v27, v4
	v_cvt_pk_bf16_f32 v4, v4, s0
	ds_write_b16 v119, v4 offset:12240
	v_mul_f32_e32 v4, 0x3fb8aa3b, v30
	v_exp_f32_e32 v4, v4
	s_nop 0
	v_mul_f32_e32 v5, v105, v4
	v_rcp_f32_e32 v4, v4
	v_cvt_pk_bf16_f32 v5, v5, s0
	ds_write_b16 v119, v5 offset:3808
	v_fmamk_f32 v105, v124, 0x3f317218, v104
	v_mul_f32_e32 v4, v22, v4
	v_cvt_pk_bf16_f32 v4, v4, s0
	ds_write_b16 v119, v4 offset:12512
	v_mul_f32_e32 v4, 0x3fb8aa3b, v31
	v_exp_f32_e32 v4, v4
	s_nop 0
	v_mul_f32_e32 v5, v106, v4
	v_rcp_f32_e32 v4, v4
	v_cvt_pk_bf16_f32 v5, v5, s0
	ds_write_b16 v119, v5 offset:4080
	v_fmamk_f32 v106, v125, 0x3f317218, v105
	v_mul_f32_e32 v4, v23, v4
	v_cvt_pk_bf16_f32 v4, v4, s0
	ds_write_b16 v119, v4 offset:12784
	v_mul_f32_e32 v4, 0x3fb8aa3b, v102
	v_exp_f32_e32 v4, v4
	s_nop 0
	v_mul_f32_e32 v5, v107, v4
	v_rcp_f32_e32 v4, v4
	v_cvt_pk_bf16_f32 v5, v5, s0
	ds_write_b16 v119, v5 offset:4352
	v_fmamk_f32 v107, v131, 0x3f317218, v106
	v_mul_f32_e32 v4, v32, v4
; #define GAS __attribute__((address_space(1)))
; #define LAS __attribute__((address_space(3)))
; DI unsigned pk2(float lo, float hi) { f32x2 v = {lo, hi}; bf16x2_t b = __builtin_convertvector(v, bf16x2_t); return __builtin_bit_cast(unsigned, b); }
; DI float fexp(float x) { return __builtin_amdgcn_exp2f(x * 1.4426950408889634f); }
; DI float frcp(float x) { return __builtin_amdgcn_rcpf(x); }
; DI void hgrn_prep_job(const Frame& F, int job, int layer, LAS unsigned char* scr) {
;     ...
;         ((GAS float*)he)[dk] = fexp(bsum);
; #pragma unroll
;         for (int t = 0; t < 32; ++t) {
;             const float e = fexp(bq[t]);
;             *(LAS bf16*)(QL + t * 272 + dk * 2) = (bf16)(pk2(qv[t] * e, 0.f) & 0xffffu);
;             *(LAS bf16*)(KL + t * 272 + dk * 2) = (bf16)(pk2(kv[t] * frcp(e), 0.f) & 0xffffu);
;             kv[t] = kv[t] * fexp(bsum - bq[t]);
;         }
	v_cvt_pk_bf16_f32 v4, v4, s0
	ds_write_b16 v119, v4 offset:13056
	v_mul_f32_e32 v4, 0x3fb8aa3b, v104
	v_exp_f32_e32 v4, v4
	s_nop 0
	v_mul_f32_e32 v5, v108, v4
	v_rcp_f32_e32 v4, v4
	v_cvt_pk_bf16_f32 v5, v5, s0
	ds_write_b16 v119, v5 offset:4624
	v_fmamk_f32 v108, v132, 0x3f317218, v107
	v_mul_f32_e32 v4, v33, v4
	v_cvt_pk_bf16_f32 v4, v4, s0
	ds_write_b16 v119, v4 offset:13328
	v_mul_f32_e32 v4, 0x3fb8aa3b, v105
	v_exp_f32_e32 v4, v4
	v_fmamk_f32 v74, v74, 0x3f317218, v108
	v_fmamk_f32 v76, v76, 0x3f317218, v74
	v_mul_f32_e32 v5, v109, v4
	v_rcp_f32_e32 v4, v4
	v_cvt_pk_bf16_f32 v5, v5, s0
	ds_write_b16 v119, v5 offset:4896
	v_fmamk_f32 v109, v135, 0x3f317218, v76
	v_mul_f32_e32 v4, v36, v4
	v_cvt_pk_bf16_f32 v4, v4, s0
	ds_write_b16 v119, v4 offset:13600
	v_mul_f32_e32 v4, 0x3fb8aa3b, v106
	v_exp_f32_e32 v4, v4
	s_nop 0
	v_mul_f32_e32 v5, v110, v4
	v_rcp_f32_e32 v4, v4
	v_cvt_pk_bf16_f32 v5, v5, s0
	ds_write_b16 v119, v5 offset:5168
	v_fmamk_f32 v110, v136, 0x3f317218, v109
	v_mul_f32_e32 v4, v37, v4
	v_cvt_pk_bf16_f32 v4, v4, s0
	ds_write_b16 v119, v4 offset:13872
	v_mul_f32_e32 v4, 0x3fb8aa3b, v107
	v_exp_f32_e32 v4, v4
	v_fmamk_f32 v91, v91, 0x3f317218, v110
	v_fmamk_f32 v99, v99, 0x3f317218, v91
	v_fmamk_f32 v101, v101, 0x3f317218, v99
	v_mul_f32_e32 v5, v111, v4
	v_rcp_f32_e32 v4, v4
	v_cvt_pk_bf16_f32 v5, v5, s0
	ds_write_b16 v119, v5 offset:5440
	v_fmamk_f32 v103, v103, 0x3f317218, v101
	v_mul_f32_e32 v4, v24, v4
	v_cvt_pk_bf16_f32 v4, v4, s0
	ds_write_b16 v119, v4 offset:14144
	v_mul_f32_e32 v4, 0x3fb8aa3b, v108
	v_exp_f32_e32 v4, v4
	v_fmamk_f32 v46, v46, 0x3f317218, v103
	v_fmamk_f32 v47, v47, 0x3f317218, v46
	v_sub_f32_e32 v6, v47, v7
	v_mul_f32_e32 v5, v112, v4
	v_rcp_f32_e32 v4, v4
	v_cvt_pk_bf16_f32 v5, v5, s0
	ds_write_b16 v119, v5 offset:5712
	v_sub_f32_e32 v7, v47, v130
	v_mul_f32_e32 v4, v25, v4
	v_cvt_pk_bf16_f32 v4, v4, s0
	ds_write_b16 v119, v4 offset:14416
	v_mul_f32_e32 v4, 0x3fb8aa3b, v74
	v_exp_f32_e32 v4, v4
	v_mul_f32_e32 v6, 0x3fb8aa3b, v6
	v_mul_f32_e32 v7, 0x3fb8aa3b, v7
	v_exp_f32_e32 v6, v6
	v_mul_f32_e32 v5, v113, v4
	v_rcp_f32_e32 v4, v4
	v_cvt_pk_bf16_f32 v5, v5, s0
	ds_write_b16 v119, v5 offset:5984
	v_exp_f32_e32 v7, v7
	v_mul_f32_e32 v4, v40, v4
	v_cvt_pk_bf16_f32 v4, v4, s0
	ds_write_b16 v119, v4 offset:14688
	v_mul_f32_e32 v4, 0x3fb8aa3b, v76
	v_exp_f32_e32 v4, v4
	v_pk_mul_f32 v[6:7], v[10:11], v[6:7]
	v_sub_f32_e32 v10, v47, v133
	v_sub_f32_e32 v11, v47, v134
	v_mul_f32_e32 v5, v114, v4
	v_rcp_f32_e32 v4, v4
	v_cvt_pk_bf16_f32 v5, v5, s0
	ds_write_b16 v119, v5 offset:6256
	v_mul_f32_e32 v10, 0x3fb8aa3b, v10
	v_mul_f32_e32 v4, v41, v4
	v_cvt_pk_bf16_f32 v4, v4, s0
	ds_write_b16 v119, v4 offset:14960
	v_mul_f32_e32 v4, 0x3fb8aa3b, v109
	v_exp_f32_e32 v4, v4
	v_mul_f32_e32 v11, 0x3fb8aa3b, v11
	v_exp_f32_e32 v10, v10
	v_exp_f32_e32 v11, v11
	v_mul_f32_e32 v5, v115, v4
	v_rcp_f32_e32 v4, v4
	v_cvt_pk_bf16_f32 v5, v5, s0
	ds_write_b16 v119, v5 offset:6528
	v_pk_mul_f32 v[8:9], v[8:9], v[10:11]
	v_mul_f32_e32 v4, v38, v4
	v_cvt_pk_bf16_f32 v4, v4, s0
	ds_write_b16 v119, v4 offset:15232
	v_mul_f32_e32 v4, 0x3fb8aa3b, v110
	v_exp_f32_e32 v4, v4
	v_sub_f32_e32 v10, v47, v75
	v_sub_f32_e32 v11, v47, v77
	v_mul_f32_e32 v10, 0x3fb8aa3b, v10
	v_mul_f32_e32 v5, v116, v4
	v_rcp_f32_e32 v4, v4
	v_cvt_pk_bf16_f32 v5, v5, s0
	ds_write_b16 v119, v5 offset:6800
	v_mul_f32_e32 v11, 0x3fb8aa3b, v11
	v_mul_f32_e32 v4, v39, v4
	v_cvt_pk_bf16_f32 v4, v4, s0
	ds_write_b16 v119, v4 offset:15504
	v_mul_f32_e32 v4, 0x3fb8aa3b, v91
	v_exp_f32_e32 v4, v4
	v_exp_f32_e32 v10, v10
	v_exp_f32_e32 v11, v11
	v_mul_f32_e32 v5, v118, v4
	v_rcp_f32_e32 v4, v4
	v_cvt_pk_bf16_f32 v5, v5, s0
	ds_write_b16 v119, v5 offset:7072
	v_pk_mul_f32 v[10:11], v[16:17], v[10:11]
	v_mul_f32_e32 v4, v34, v4
	v_cvt_pk_bf16_f32 v4, v4, s0
	ds_write_b16 v119, v4 offset:15776
	v_mul_f32_e32 v4, 0x3fb8aa3b, v99
	v_exp_f32_e32 v4, v4
	v_sub_f32_e32 v16, v47, v138
	v_sub_f32_e32 v17, v47, v137
	v_mul_f32_e32 v16, 0x3fb8aa3b, v16
	v_mul_f32_e32 v5, v121, v4
	v_rcp_f32_e32 v4, v4
	v_cvt_pk_bf16_f32 v5, v5, s0
	ds_write_b16 v119, v5 offset:7344
	v_mul_f32_e32 v17, 0x3fb8aa3b, v17
	v_mul_f32_e32 v4, v35, v4
	v_cvt_pk_bf16_f32 v4, v4, s0
	ds_write_b16 v119, v4 offset:16048
	v_mul_f32_e32 v4, 0x3fb8aa3b, v101
	v_exp_f32_e32 v4, v4
	v_exp_f32_e32 v16, v16
	v_exp_f32_e32 v17, v17
	v_mul_f32_e32 v5, v122, v4
	v_rcp_f32_e32 v4, v4
	v_cvt_pk_bf16_f32 v5, v5, s0
	ds_write_b16 v119, v5 offset:7616
	v_pk_mul_f32 v[16:17], v[26:27], v[16:17]
	v_mul_f32_e32 v4, v42, v4
	v_cvt_pk_bf16_f32 v4, v4, s0
	ds_write_b16 v119, v4 offset:16320
	v_mul_f32_e32 v4, 0x3fb8aa3b, v103
	v_exp_f32_e32 v4, v4
	v_sub_f32_e32 v26, v47, v107
	v_sub_f32_e32 v27, v47, v108
	v_mul_f32_e32 v26, 0x3fb8aa3b, v26
	v_mul_f32_e32 v5, v123, v4
	v_rcp_f32_e32 v4, v4
	v_cvt_pk_bf16_f32 v5, v5, s0
	ds_write_b16 v119, v5 offset:7888
	v_sub_f32_e32 v5, v47, v129
	v_mul_f32_e32 v4, v43, v4
	v_cvt_pk_bf16_f32 v4, v4, s0
	ds_write_b16 v119, v4 offset:16592
	v_mul_f32_e32 v4, 0x3fb8aa3b, v47
	v_exp_f32_e32 v111, v4
	v_sub_f32_e32 v4, v47, v128
	v_mul_f32_e32 v4, 0x3fb8aa3b, v4
	v_mul_f32_e32 v5, 0x3fb8aa3b, v5
	v_exp_f32_e32 v4, v4
	v_exp_f32_e32 v5, v5
	global_store_dword v[12:13], v111, off
	v_sub_f32_e32 v12, v47, v29
	v_sub_f32_e32 v13, v47, v28
	v_pk_mul_f32 v[4:5], v[14:15], v[4:5]
	v_sub_f32_e32 v14, v47, v95
	v_sub_f32_e32 v15, v47, v98
	v_mul_f32_e32 v14, 0x3fb8aa3b, v14
	v_mul_f32_e32 v15, 0x3fb8aa3b, v15
	v_exp_f32_e32 v14, v14
	v_exp_f32_e32 v15, v15
	v_mul_f32_e32 v12, 0x3fb8aa3b, v12
	v_mul_f32_e32 v13, 0x3fb8aa3b, v13
	v_exp_f32_e32 v12, v12
	v_pk_mul_f32 v[14:15], v[18:19], v[14:15]
; #define GAS __attribute__((address_space(1)))
; DI unsigned pk2(float lo, float hi) { f32x2 v = {lo, hi}; bf16x2_t b = __builtin_convertvector(v, bf16x2_t); return __builtin_bit_cast(unsigned, b); }
; DI void hgrn_prep_job(const Frame& F, int job, int layer, LAS unsigned char* scr) {
;     ...
; #pragma unroll
;         for (int g = 0; g < 4; ++g) {
;             v4u w; w.x = pk2(kv[permk(g, 0)], kv[permk(g, 1)]); w.y = pk2(kv[permk(g, 2)], kv[permk(g, 3)]); w.z = pk2(kv[permk(g, 4)], kv[permk(g, 5)]); w.w = pk2(kv[permk(g, 6)], kv[permk(g, 7)]);
;             *(GAS v4u*)(hk + (((dk >> 4) * 64) + (dk & 15) + 16 * g) * 16) = w;
;         }
; #pragma unroll
;         for (int g = 0; g < 4; ++g) {
;             v4u w; w.x = ve[permk(g, 0)] | ((unsigned)ve[permk(g, 1)] << 16); w.y = ve[permk(g, 2)] | ((unsigned)ve[permk(g, 3)] << 16);
;             w.z = ve[permk(g, 4)] | ((unsigned)ve[permk(g, 5)] << 16); w.w = ve[permk(g, 6)] | ((unsigned)ve[permk(g, 7)] << 16);
;             *(GAS v4u*)(hv + (((dk >> 4) * 64) + (dk & 15) + 16 * g) * 16) = w;
;         }
	v_sub_f32_e32 v18, v47, v30
	v_sub_f32_e32 v19, v47, v31
	v_sub_f32_e32 v30, v47, v91
	v_sub_f32_e32 v31, v47, v99
	v_mul_f32_e32 v30, 0x3fb8aa3b, v30
	v_mul_f32_e32 v31, 0x3fb8aa3b, v31
	v_exp_f32_e32 v30, v30
	v_exp_f32_e32 v31, v31
	v_exp_f32_e32 v13, v13
	v_mul_f32_e32 v18, 0x3fb8aa3b, v18
	v_mul_f32_e32 v19, 0x3fb8aa3b, v19
	v_pk_mul_f32 v[30:31], v[34:35], v[30:31]
	v_mul_f32_e32 v34, 0x3fb8aa3b, v46
	v_exp_f32_e32 v34, v34
	v_exp_f32_e32 v18, v18
	v_exp_f32_e32 v19, v19
	v_mul_f32_e32 v27, 0x3fb8aa3b, v27
	v_mul_f32_e32 v35, v117, v34
	v_cvt_pk_bf16_f32 v35, v35, s0
	ds_write_b16 v119, v35 offset:8160
	v_mul_f32_e32 v35, v120, v111
	v_cvt_pk_bf16_f32 v35, v35, s0
	v_pk_mul_f32 v[12:13], v[20:21], v[12:13]
	v_sub_f32_e32 v20, v47, v102
	v_sub_f32_e32 v21, v47, v104
	v_exp_f32_e32 v26, v26
	v_exp_f32_e32 v27, v27
	v_rcp_f32_e32 v34, v34
	ds_write_b16 v119, v35 offset:8432
	v_rcp_f32_e32 v35, v111
	v_mul_f32_e32 v20, 0x3fb8aa3b, v20
	v_mul_f32_e32 v21, 0x3fb8aa3b, v21
	v_pk_mul_f32 v[18:19], v[22:23], v[18:19]
	v_exp_f32_e32 v20, v20
	v_exp_f32_e32 v21, v21
	v_sub_f32_e32 v22, v47, v105
	v_sub_f32_e32 v23, v47, v106
	v_mul_f32_e32 v22, 0x3fb8aa3b, v22
	v_mul_f32_e32 v23, 0x3fb8aa3b, v23
	v_exp_f32_e32 v22, v22
	v_exp_f32_e32 v23, v23
	v_pk_mul_f32 v[24:25], v[24:25], v[26:27]
	v_sub_f32_e32 v26, v47, v74
	v_sub_f32_e32 v27, v47, v76
	v_mul_f32_e32 v34, v44, v34
	v_mul_f32_e32 v35, v45, v35
	v_mul_f32_e32 v26, 0x3fb8aa3b, v26
	v_mul_f32_e32 v27, 0x3fb8aa3b, v27
	v_sub_f32_e32 v28, v47, v109
	v_sub_f32_e32 v29, v47, v110
	v_cvt_pk_bf16_f32 v34, v34, s0
	v_cvt_pk_bf16_f32 v35, v35, s0
	v_pk_mul_f32 v[20:21], v[32:33], v[20:21]
	v_exp_f32_e32 v26, v26
	v_exp_f32_e32 v27, v27
	v_mul_f32_e32 v28, 0x3fb8aa3b, v28
	v_mul_f32_e32 v29, 0x3fb8aa3b, v29
	v_sub_f32_e32 v32, v47, v101
	v_sub_f32_e32 v33, v47, v103
	ds_write_b16 v119, v34 offset:16864
	v_sub_f32_e32 v34, v47, v46
	ds_write_b16 v119, v35 offset:17136
	v_sub_f32_e32 v35, v47, v47
	v_exp_f32_e32 v28, v28
	v_exp_f32_e32 v29, v29
	v_mul_f32_e32 v32, 0x3fb8aa3b, v32
	v_mul_f32_e32 v33, 0x3fb8aa3b, v33
	v_mul_f32_e32 v34, 0x3fb8aa3b, v34
	v_mul_f32_e32 v35, 0x3fb8aa3b, v35
	v_pk_mul_f32 v[22:23], v[36:37], v[22:23]
	v_exp_f32_e32 v32, v32
	v_exp_f32_e32 v33, v33
	v_exp_f32_e32 v34, v34
	v_exp_f32_e32 v35, v35
	v_lshlrev_b32_e32 v36, 2, v96
	s_movk_i32 s0, 0x1c0
	v_and_or_b32 v36, v36, s0, v49
	v_pk_mul_f32 v[26:27], v[40:41], v[26:27]
	v_lshlrev_b32_e32 v36, 4, v36
	v_cvt_pk_bf16_f32 v4, v4, v5
	v_cvt_pk_bf16_f32 v5, v6, v7
	v_cvt_pk_bf16_f32 v6, v20, v21
	v_cvt_pk_bf16_f32 v7, v22, v23
	v_pk_mul_f32 v[28:29], v[38:39], v[28:29]
	global_store_dwordx4 v36, v[4:7], s[60:61]
	v_pk_mul_f32 v[32:33], v[42:43], v[32:33]
	v_pk_mul_f32 v[34:35], v[44:45], v[34:35]
	v_cvt_pk_bf16_f32 v4, v8, v9
	v_cvt_pk_bf16_f32 v5, v10, v11
	v_cvt_pk_bf16_f32 v6, v24, v25
	v_cvt_pk_bf16_f32 v7, v26, v27
	global_store_dwordx4 v36, v[4:7], s[60:61] offset:256
	s_mov_b32 s0, 64
	s_nop 0
	v_cvt_pk_bf16_f32 v4, v12, v13
	v_cvt_pk_bf16_f32 v5, v14, v15
	v_cvt_pk_bf16_f32 v6, v28, v29
	v_cvt_pk_bf16_f32 v7, v30, v31
	global_store_dwordx4 v36, v[4:7], s[60:61] offset:512
	s_nop 1
	v_cvt_pk_bf16_f32 v4, v16, v17
	v_cvt_pk_bf16_f32 v5, v18, v19
	v_cvt_pk_bf16_f32 v6, v32, v33
	v_cvt_pk_bf16_f32 v7, v34, v35
	global_store_dwordx4 v36, v[4:7], s[60:61] offset:768
	s_waitcnt vmcnt(20)
	s_nop 0
	v_lshl_or_b32 v4, v78, 16, v58
	s_waitcnt vmcnt(19)
	v_lshl_or_b32 v5, v79, 16, v59
	s_waitcnt vmcnt(18)
	v_lshl_or_b32 v6, v80, 16, v66
	s_waitcnt vmcnt(17)
	v_lshl_or_b32 v7, v81, 16, v67
	global_store_dwordx4 v36, v[4:7], s[62:63]
	s_waitcnt vmcnt(17)
	s_nop 0
	v_lshl_or_b32 v4, v82, 16, v60
	s_waitcnt vmcnt(16)
	v_lshl_or_b32 v5, v83, 16, v61
	s_waitcnt vmcnt(15)
	v_lshl_or_b32 v6, v84, 16, v68
	s_waitcnt vmcnt(14)
	v_lshl_or_b32 v7, v85, 16, v69
	global_store_dwordx4 v36, v[4:7], s[62:63] offset:256
	s_waitcnt vmcnt(14)
	s_nop 0
	v_lshl_or_b32 v4, v86, 16, v62
	s_waitcnt vmcnt(13)
	v_lshl_or_b32 v5, v87, 16, v63
	s_waitcnt vmcnt(12)
	v_lshl_or_b32 v6, v88, 16, v70
	s_waitcnt vmcnt(11)
	v_lshl_or_b32 v7, v89, 16, v71
	global_store_dwordx4 v36, v[4:7], s[62:63] offset:512
	s_waitcnt vmcnt(11)
	s_nop 0
	v_lshl_or_b32 v4, v90, 16, v64
	s_waitcnt vmcnt(10)
	v_lshl_or_b32 v5, v92, 16, v65
	s_waitcnt vmcnt(9)
	v_lshl_or_b32 v6, v93, 16, v72
	s_waitcnt vmcnt(8)
	v_lshl_or_b32 v7, v94, 16, v73
	global_store_dwordx4 v36, v[4:7], s[62:63] offset:768
	s_cbranch_vccnz .LBB0_810
; #define GAS __attribute__((address_space(1)))
; #define LAS __attribute__((address_space(3)))
; #define LDS_WAIT() asm volatile("s_waitcnt lgkmcnt(0)" ::: "memory")
; DI void hgrn_prep_job(const Frame& F, int job, int layer, LAS unsigned char* scr) {
;     ...
;     LDS_WAIT(); asm volatile("" ::: "memory");
;     const int r = lane & 15, g = lane >> 4;
; #pragma unroll
;     for (int mt = 0; mt < 2; ++mt)
; #pragma unroll
;         for (int kb = 0; kb < 4; ++kb) {
;             const LAS unsigned char* p = QL + (16 * mt + r) * 272 + (32 * kb + 4 * g) * 2;
;             const v2u lo = *(const LAS v2u*)p, hi = *(const LAS v2u*)(p + 32);
;             *(GAS v4u*)(hq + ((mt * 4 + kb) * 64 + lane) * 16) = (v4u){lo.x, lo.y, hi.x, hi.y};
;         }
;     f32x4 acc[2][2];
; #pragma unroll
;     for (int mt = 0; mt < 2; ++mt)
; #pragma unroll
;         for (int nt = 0; nt < 2; ++nt) acc[mt][nt] = (f32x4){0.f, 0.f, 0.f, 0.f};
; #pragma unroll
;     for (int ks = 0; ks < 4; ++ks) {
;         bf16x8 af[2], bfr[2];
; #pragma unroll
;         for (int mt = 0; mt < 2; ++mt) { af[mt] = *(const LAS bf16x8*)(QL + (16 * mt + r) * 272 + (32 * ks + 8 * g) * 2); bfr[mt] = *(const LAS bf16x8*)(KL + (16 * mt + r) * 272 + (32 * ks + 8 * g) * 2); }
; #pragma unroll
;         for (int mt = 0; mt < 2; ++mt)
; #pragma unroll
;             for (int nt = 0; nt < 2; ++nt) acc[mt][nt] = __builtin_amdgcn_mfma_f32_16x16x32_bf16(af[mt], bfr[nt], acc[mt][nt], 0, 0, 0);
;     }
;     LDS_WAIT(); asm volatile("" ::: "memory");
; #pragma unroll
;     for (int mt = 0; mt < 2; ++mt)
; #pragma unroll
;         for (int nt = 0; nt < 2; ++nt)
; #pragma unroll
;             for (int i = 0; i < 4; ++i) { const int t = 16 * mt + 4 * g + i, s = 16 * nt + r;
;                 *(LAS bf16*)(KL + t * 80 + s * 2) = (bf16)(pk2(s <= t ? acc[mt][nt][i] : 0.f, 0.f) & 0xffffu); }
;     LDS_WAIT(); asm volatile("" ::: "memory");
; #pragma unroll
;     for (int mt = 0; mt < 2; ++mt) {
;         const LAS unsigned char* p = KL + (16 * mt + r) * 80 + (4 * g) * 2;
;         const v2u lo = *(const LAS v2u*)p, hi = *(const LAS v2u*)(p + 32);
;         *(GAS v4u*)(ha + (mt * 64 + lane) * 16) = (v4u){lo.x, lo.y, hi.x, hi.y};
;     }
;     LDS_WAIT(); asm volatile("" ::: "memory");
	s_waitcnt lgkmcnt(0)
	v_add_u32_e32 v10, v50, v51
	ds_read2_b64 v[4:7], v10 offset1:4
	v_lshl_add_u64 v[8:9], v[0:1], 0, s[58:59]
	s_movk_i32 s0, 0x1000
	s_waitcnt lgkmcnt(0)
	global_store_dwordx4 v[8:9], v[4:7], off
	ds_read2_b64 v[4:7], v10 offset0:8 offset1:12
	s_waitcnt lgkmcnt(0)
	global_store_dwordx4 v[8:9], v[4:7], off offset:1024
	ds_read2_b64 v[4:7], v10 offset0:16 offset1:20
	s_waitcnt lgkmcnt(0)
	global_store_dwordx4 v[8:9], v[4:7], off offset:2048
	ds_read2_b64 v[4:7], v10 offset0:24 offset1:28
	v_add_u32_e32 v10, 0x1000, v10
	s_waitcnt lgkmcnt(0)
	global_store_dwordx4 v[8:9], v[4:7], off offset:3072
	ds_read2_b64 v[4:7], v10 offset0:32 offset1:36
	v_add_co_u32_e32 v8, vcc, s0, v8
	s_nop 1
	v_addc_co_u32_e32 v9, vcc, 0, v9, vcc
	s_waitcnt lgkmcnt(0)
	global_store_dwordx4 v[8:9], v[4:7], off
	ds_read2_b64 v[4:7], v10 offset0:40 offset1:44
	s_waitcnt lgkmcnt(0)
	global_store_dwordx4 v[8:9], v[4:7], off offset:1024
	ds_read2_b64 v[4:7], v10 offset0:48 offset1:52
	s_waitcnt lgkmcnt(0)
	global_store_dwordx4 v[8:9], v[4:7], off offset:2048
	ds_read2_b64 v[4:7], v10 offset0:56 offset1:60
	s_waitcnt lgkmcnt(0)
	global_store_dwordx4 v[8:9], v[4:7], off offset:3072
	ds_read_b128 v[4:7], v56
	ds_read_b128 v[8:11], v56 offset:8704
	ds_read_b128 v[12:15], v56 offset:4352
	ds_read_b128 v[16:19], v56 offset:13056
	s_waitcnt lgkmcnt(2)
	v_mfma_f32_16x16x32_bf16 v[4:7], v[4:7], v[8:11], 0
	s_waitcnt lgkmcnt(1)
	v_mfma_f32_16x16x32_bf16 v[8:11], v[12:15], v[8:11], 0
	s_waitcnt lgkmcnt(0)
	v_mfma_f32_16x16x32_bf16 v[12:15], v[12:15], v[16:19], 0
	ds_read_b128 v[16:19], v56 offset:64
	ds_read_b128 v[20:23], v56 offset:8768
	ds_read_b128 v[24:27], v56 offset:4416
	ds_read_b128 v[28:31], v56 offset:13120
	s_waitcnt lgkmcnt(2)
	v_mfma_f32_16x16x32_bf16 v[4:7], v[16:19], v[20:23], v[4:7]
	s_waitcnt lgkmcnt(1)
	v_mfma_f32_16x16x32_bf16 v[8:11], v[24:27], v[20:23], v[8:11]
	s_waitcnt lgkmcnt(0)
	v_mfma_f32_16x16x32_bf16 v[12:15], v[24:27], v[28:31], v[12:15]
	ds_read_b128 v[16:19], v56 offset:128
	ds_read_b128 v[20:23], v56 offset:8832
	ds_read_b128 v[24:27], v56 offset:4480
	ds_read_b128 v[28:31], v56 offset:13184
	s_waitcnt lgkmcnt(2)
	v_mfma_f32_16x16x32_bf16 v[4:7], v[16:19], v[20:23], v[4:7]
	s_waitcnt lgkmcnt(1)
	v_mfma_f32_16x16x32_bf16 v[8:11], v[24:27], v[20:23], v[8:11]
	s_waitcnt lgkmcnt(0)
	v_mfma_f32_16x16x32_bf16 v[12:15], v[24:27], v[28:31], v[12:15]
	ds_read_b128 v[16:19], v56 offset:192
	ds_read_b128 v[20:23], v56 offset:8896
	ds_read_b128 v[24:27], v56 offset:4544
	ds_read_b128 v[28:31], v56 offset:13248
	s_waitcnt lgkmcnt(0)
	s_waitcnt lgkmcnt(2)
	v_mfma_f32_16x16x32_bf16 v[4:7], v[16:19], v[20:23], v[4:7]
	v_add_u32_e32 v16, v52, v53
	s_waitcnt lgkmcnt(1)
	v_mfma_f32_16x16x32_bf16 v[8:11], v[24:27], v[20:23], v[8:11]
	s_waitcnt lgkmcnt(0)
	v_mfma_f32_16x16x32_bf16 v[12:15], v[24:27], v[28:31], v[12:15]
	s_nop 2
	v_cvt_pk_bf16_f32 v4, v4, s0
	v_cndmask_b32_e64 v4, v4, 0, s[40:41]
	ds_write_b16 v16, v4 offset:8704
	v_cvt_pk_bf16_f32 v4, v5, s0
	v_cndmask_b32_e64 v4, v4, 0, s[42:43]
	v_add_u32_e32 v5, v52, v54
	ds_write_b16 v5, v4 offset:8704
	v_cvt_pk_bf16_f32 v4, v6, s0
	v_cndmask_b32_e64 v4, v4, 0, s[44:45]
	ds_write_b16 v5, v4 offset:8784
	v_cvt_pk_bf16_f32 v4, v7, s0
	v_cndmask_b32_e64 v4, v4, 0, s[46:47]
	ds_write_b16 v5, v4 offset:8864
	v_add_u32_e32 v4, v55, v53
	v_add_u32_e32 v6, v55, v54
	v_cvt_pk_bf16_f32 v7, v8, s0
	ds_write_b16 v4, v97 offset:8704
	ds_write_b16 v6, v97 offset:8704
	ds_write_b16 v6, v97 offset:8784
	ds_write_b16 v6, v97 offset:8864
	ds_write_b16 v16, v7 offset:9984
	v_cvt_pk_bf16_f32 v7, v9, s0
	ds_write_b16 v5, v7 offset:9984
	v_cvt_pk_bf16_f32 v7, v10, s0
	ds_write_b16 v5, v7 offset:10064
	v_cvt_pk_bf16_f32 v7, v11, s0
	ds_write_b16 v5, v7 offset:10144
	v_cvt_pk_bf16_f32 v5, v12, s0
	v_cndmask_b32_e64 v5, v5, 0, s[40:41]
	ds_write_b16 v4, v5 offset:9984
	v_cvt_pk_bf16_f32 v4, v13, s0
	v_cndmask_b32_e64 v4, v4, 0, s[48:49]
	ds_write_b16 v6, v4 offset:9984
	v_cvt_pk_bf16_f32 v4, v14, s0
	v_cndmask_b32_e64 v4, v4, 0, s[50:51]
	ds_write_b16 v6, v4 offset:10064
	v_cvt_pk_bf16_f32 v4, v15, s0
	v_cndmask_b32_e64 v4, v4, 0, s[52:53]
	ds_write_b16 v6, v4 offset:10144
	s_waitcnt lgkmcnt(0)
	v_add_u32_e32 v10, 0x2000, v57
	ds_read2_b64 v[4:7], v10 offset0:64 offset1:68
	s_lshl_b64 s[0:1], s[54:55], 11
	v_lshl_add_u64 v[8:9], v[2:3], 0, s[0:1]
	v_readlane_b32 s0, v253, 34
	s_add_i32 s30, s30, s0
	s_waitcnt lgkmcnt(0)
	global_store_dwordx4 v[8:9], v[4:7], off
	ds_read2_b64 v[4:7], v10 offset0:224 offset1:228
	s_cmpk_gt_i32 s30, 0x5ff
	v_readlane_b32 s1, v253, 35
	s_waitcnt lgkmcnt(0)
	global_store_dwordx4 v[8:9], v[4:7], off offset:1024
	s_waitcnt lgkmcnt(0)
	s_cbranch_scc0 .LBB0_809
